# band attention: next item's inputs requested in the last half-step of the current item; item-start drains kept (run 1)
# speedup vs baseline: 1.0030x; 1.0011x over previous
.LBB0_1038:
	v_mov_b32_e32 v0, v135
	s_nop 1
	v_permlane16_swap_b32_e32 v135, v0
	v_add_f32_e32 v0, v135, v0
	v_mov_b32_e32 v1, v0
	s_nop 1
	v_permlane32_swap_b32_e32 v0, v1
	s_lshl_b64 s[0:1], s[22:23], 11
	v_add_f32_e32 v2, v0, v1
	s_add_u32 s0, s70, s0
	v_div_scale_f32 v3, s[2:3], v2, v2, 1.0
	s_addc_u32 s1, s71, s1
	v_rcp_f32_e32 v6, v3
	s_add_u32 s0, s0, s24
	s_addc_u32 s1, s1, s25
	v_mov_b32_e32 v133, v153
	v_lshl_add_u64 v[0:1], s[0:1], 0, v[132:133]
	v_mov_b32_e32 v135, v153
	v_lshl_add_u64 v[4:5], v[0:1], 0, v[134:135]
	v_fma_f32 v0, -v3, v6, 1.0
	v_fmac_f32_e32 v6, v0, v6
	v_div_scale_f32 v0, vcc, 1.0, v2, 1.0
	v_mul_f32_e32 v1, v0, v6
	v_fma_f32 v7, -v3, v1, v0
	v_fmac_f32_e32 v1, v7, v6
	v_fma_f32 v0, -v3, v1, v0
	v_div_fmas_f32 v0, v0, v6, v1
	v_div_fixup_f32 v6, v0, v2, 1.0
	v_pk_mul_f32 v[0:1], v[56:57], v[6:7] op_sel_hi:[1,0]
	v_pk_mul_f32 v[2:3], v[58:59], v[6:7] op_sel_hi:[1,0]
	v_cvt_pk_bf16_f32 v0, v0, v1
	v_cvt_pk_bf16_f32 v1, v2, v3
	v_pk_mul_f32 v[2:3], v[60:61], v[6:7] op_sel_hi:[1,0]
	v_pk_mul_f32 v[10:11], v[62:63], v[6:7] op_sel_hi:[1,0]
	v_mov_b32_e32 v137, v153
	v_cvt_pk_bf16_f32 v2, v2, v3
	v_cvt_pk_bf16_f32 v3, v10, v11
	v_lshl_add_u64 v[8:9], v[4:5], 0, v[136:137]
	v_permlane16_swap_b32_e32 v0, v2
	v_permlane16_swap_b32_e32 v1, v3
	global_store_dwordx4 v[8:9], v[0:3], off
	v_mov_b32_e32 v139, v153
	v_lshl_add_u64 v[4:5], v[4:5], 0, v[138:139]
	v_pk_mul_f32 v[0:1], v[52:53], v[6:7] op_sel_hi:[1,0]
	v_pk_mul_f32 v[2:3], v[54:55], v[6:7] op_sel_hi:[1,0]
	v_cvt_pk_bf16_f32 v0, v0, v1
	v_cvt_pk_bf16_f32 v1, v2, v3
	v_pk_mul_f32 v[2:3], v[44:45], v[6:7] op_sel_hi:[1,0]
	v_pk_mul_f32 v[6:7], v[46:47], v[6:7] op_sel_hi:[1,0]
	v_cvt_pk_bf16_f32 v2, v2, v3
	v_cvt_pk_bf16_f32 v3, v6, v7
	v_mov_b32_e32 v6, v131
	s_nop 1
	v_permlane16_swap_b32_e32 v131, v6
	v_add_f32_e32 v6, v131, v6
	v_mov_b32_e32 v7, v6
	s_nop 1
	v_permlane32_swap_b32_e32 v6, v7
	v_add_f32_e32 v6, v6, v7
	v_div_scale_f32 v7, s[0:1], v6, v6, 1.0
	v_rcp_f32_e32 v10, v7
	v_permlane16_swap_b32_e32 v0, v2
	v_permlane16_swap_b32_e32 v1, v3
	global_store_dwordx4 v[8:9], v[0:3], off offset:64
	s_add_i32 s26, s26, s90
	s_cmpk_gt_i32 s26, 0x5ff
	v_fma_f32 v0, -v7, v10, 1.0
	v_fmac_f32_e32 v10, v0, v10
	v_div_scale_f32 v0, vcc, 1.0, v6, 1.0
	v_mul_f32_e32 v1, v0, v10
	v_fma_f32 v2, -v7, v1, v0
	v_fmac_f32_e32 v1, v2, v10
	v_fma_f32 v0, -v7, v1, v0
	v_div_fmas_f32 v0, v0, v10, v1
	v_div_fixup_f32 v6, v0, v6, 1.0
	v_pk_mul_f32 v[0:1], v[40:41], v[6:7] op_sel_hi:[1,0]
	v_pk_mul_f32 v[2:3], v[42:43], v[6:7] op_sel_hi:[1,0]
	v_cvt_pk_bf16_f32 v0, v0, v1
	v_cvt_pk_bf16_f32 v1, v2, v3
	v_pk_mul_f32 v[2:3], v[48:49], v[6:7] op_sel_hi:[1,0]
	v_pk_mul_f32 v[8:9], v[50:51], v[6:7] op_sel_hi:[1,0]
	v_cvt_pk_bf16_f32 v2, v2, v3
	v_cvt_pk_bf16_f32 v3, v8, v9
	s_nop 0
	v_permlane16_swap_b32_e32 v0, v2
	v_permlane16_swap_b32_e32 v1, v3
	global_store_dwordx4 v[4:5], v[0:3], off
	s_nop 1
	v_pk_mul_f32 v[0:1], v[36:37], v[6:7] op_sel_hi:[1,0]
	v_pk_mul_f32 v[2:3], v[38:39], v[6:7] op_sel_hi:[1,0]
	v_cvt_pk_bf16_f32 v0, v0, v1
	v_cvt_pk_bf16_f32 v1, v2, v3
	v_pk_mul_f32 v[2:3], v[32:33], v[6:7] op_sel_hi:[1,0]
	v_pk_mul_f32 v[6:7], v[34:35], v[6:7] op_sel_hi:[1,0]
	v_cvt_pk_bf16_f32 v2, v2, v3
	v_cvt_pk_bf16_f32 v3, v6, v7
	s_nop 0
	v_permlane16_swap_b32_e32 v0, v2
	v_permlane16_swap_b32_e32 v1, v3
	global_store_dwordx4 v[4:5], v[0:3], off offset:64
	s_cbranch_scc1 .LBB0_1080
.LBB0_1039:
	s_mul_hi_i32 s3, s26, 0x2aaaaaab
	s_lshr_b32 s4, s3, 31
	s_ashr_i32 s5, s3, 1
	s_add_i32 s5, s5, s4
	s_mul_i32 s0, s5, 12
	s_sub_i32 s2, s26, s0
	s_waitcnt vmcnt(0)
	s_barrier
	s_and_saveexec_b64 s[0:1], s[36:37]
	s_cbranch_execz .LBB0_1041
	s_mul_i32 s6, s2, 0xc0
	s_ashr_i32 s7, s6, 31
	v_lshl_add_u64 v[0:1], s[6:7], 2, v[126:127]
	v_readlane_b32 s100, v250, 0
	s_cmp_lg_u32 s26, s100
	s_cbranch_scc1 .LBB0_1041
	global_load_dword v237, v[0:1], off
.LBB0_1041:
	s_or_b64 exec, exec, s[0:1]
	s_ashr_i32 s0, s3, 5
	s_add_i32 s0, s0, s4
	s_and_b32 s8, s5, 15
	s_ashr_i32 s1, s0, 31
	s_lshl_b64 s[28:29], s[0:1], 12
	s_lshl_b32 s1, s8, 8
	s_lshl_b32 s11, s8, 2
	s_or_b32 s3, s28, s1
	s_add_u32 s22, s3, s14
	s_addc_u32 s23, s29, s20
	s_mul_i32 s3, s23, 0x1400
	s_mul_hi_u32 s4, s22, 0x1400
	s_add_i32 s4, s4, s3
	s_mul_i32 s3, s22, 0x1400
	s_add_u32 s5, s60, s3
	s_addc_u32 s4, s61, s4
	s_lshl_b32 s2, s2, 6
	s_ashr_i32 s3, s2, 31
	s_lshl_b64 s[24:25], s[2:3], 1
	s_add_u32 s2, s5, s24
	s_addc_u32 s3, s4, s25
	s_add_u32 s4, s94, s24
	s_addc_u32 s5, s19, s25
	s_add_u32 s6, s31, s24
	s_addc_u32 s7, s33, s25
	s_add_i32 s9, s11, -8
	s_cmp_gt_u32 s8, 1
	s_cselect_b32 s30, s9, 0
	v_lshl_add_u64 v[0:1], s[2:3], 0, v[152:153]
	v_mov_b32_e32 v131, v153
	s_lshl_b32 s8, s30, 6
	v_lshl_add_u64 v[8:9], v[0:1], 0, v[130:131]
	s_mov_b64 s[2:3], 0x14000
	s_ashr_i32 s9, s8, 31
	v_lshl_add_u64 v[32:33], s[28:29], 0, v[114:115]
	v_lshl_add_u64 v[12:13], v[8:9], 0, s[2:3]
	s_mov_b32 s2, 0x14000
	v_lshl_add_u64 v[10:11], v[32:33], 0, s[8:9]
	v_readlane_b32 s100, v250, 0
	s_cmp_lg_u32 s26, s100
	s_cbranch_scc1 .Lcip_q01
	global_load_dwordx4 v[0:3], v[8:9], off
	global_load_dwordx4 v[4:7], v[8:9], off offset:64
.Lcip_q01:
	v_add_co_u32_e32 v8, vcc, s2, v8
	v_mad_u64_u32 v[14:15], s[2:3], v10, s40, 0
	v_mad_i32_i24 v11, v11, s40, v15
	v_or_b32_e32 v10, v14, v112
	v_lshlrev_b64 v[10:11], 1, v[10:11]
	v_addc_co_u32_e32 v9, vcc, 0, v9, vcc
	v_lshl_add_u64 v[14:15], s[4:5], 0, v[10:11]
	v_lshl_add_u64 v[10:11], s[6:7], 0, v[10:11]
	s_add_i32 s2, s11, 4
	v_readlane_b32 s100, v250, 0
	s_cmp_lg_u32 s26, s100
	s_cbranch_scc1 .Lcip_have
	v_mov_b32_e32 v230, v14
	v_mov_b32_e32 v231, v15
	v_mov_b32_e32 v232, v10
	v_mov_b32_e32 v233, v11
	s_cmp_ge_u32 s11, 8
	s_cbranch_scc0 .Lbs_noskew
	global_load_dwordx4 v[206:209], v[230:231], off
	global_load_dwordx4 v[210:213], v[232:233], off
	v_add_co_u32_e32 v230, vcc, 0x50000, v230
	s_nop 1
	v_addc_co_u32_e32 v231, vcc, 0, v231, vcc
	v_add_co_u32_e32 v232, vcc, 0x50000, v232
	s_nop 1
	v_addc_co_u32_e32 v233, vcc, 0, v233, vcc
	global_load_dwordx4 v[214:217], v[230:231], off
	global_load_dwordx4 v[218:221], v[232:233], off
	v_add_co_u32_e32 v230, vcc, 0x50000, v230
	s_nop 1
	v_addc_co_u32_e32 v231, vcc, 0, v231, vcc
	v_add_co_u32_e32 v232, vcc, 0x50000, v232
	s_nop 1
	v_addc_co_u32_e32 v233, vcc, 0, v233, vcc
	global_load_dwordx4 v[222:225], v[230:231], off
	global_load_dwordx4 v[226:229], v[232:233], off
	v_add_co_u32_e32 v230, vcc, 0x50000, v230
	s_nop 1
	v_addc_co_u32_e32 v231, vcc, 0, v231, vcc
	v_add_co_u32_e32 v232, vcc, 0x50000, v232
	s_nop 1
	v_addc_co_u32_e32 v233, vcc, 0, v233, vcc
.Lbs_noskew:
	global_load_dwordx4 v[16:19], v[230:231], off
	global_load_dwordx4 v[20:23], v[232:233], off
	v_add_co_u32_e32 v230, vcc, 0x50000, v230
	s_nop 1
	v_addc_co_u32_e32 v231, vcc, 0, v231, vcc
	v_add_co_u32_e32 v232, vcc, 0x50000, v232
	s_nop 1
	v_addc_co_u32_e32 v233, vcc, 0, v233, vcc
	global_load_dwordx4 v[8:11], v[8:9], off
	global_load_dwordx4 v[12:15], v[12:13], off offset:64
	global_load_dwordx4 v[24:27], v[230:231], off
	global_load_dwordx4 v[28:31], v[232:233], off
	s_cmp_ge_u32 s11, 8
	s_cbranch_scc0 .Lbs_nopre
	s_waitcnt vmcnt(6)
	s_branch .Lcip_pre
.Lcip_have:
	s_waitcnt vmcnt(4)
	v_mov_b32_e32 v0, v176
	v_mov_b32_e32 v1, v177
	v_mov_b32_e32 v2, v178
	v_mov_b32_e32 v3, v179
	v_mov_b32_e32 v4, v180
	v_mov_b32_e32 v5, v181
	v_mov_b32_e32 v6, v182
	v_mov_b32_e32 v7, v183
	v_mov_b32_e32 v8, v184
	v_mov_b32_e32 v9, v185
	v_mov_b32_e32 v10, v186
	v_mov_b32_e32 v11, v187
	v_mov_b32_e32 v12, v196
	v_mov_b32_e32 v13, v197
	v_mov_b32_e32 v14, v198
	v_mov_b32_e32 v15, v199
	v_mov_b32_e32 v16, v238
	v_mov_b32_e32 v17, v239
	v_mov_b32_e32 v18, v240
	v_mov_b32_e32 v19, v241
	v_mov_b32_e32 v20, v242
	v_mov_b32_e32 v21, v243
	v_mov_b32_e32 v22, v244
	v_mov_b32_e32 v23, v245
	v_mov_b32_e32 v24, v230
	v_mov_b32_e32 v25, v231
	v_mov_b32_e32 v26, v232
	v_mov_b32_e32 v27, v233
	v_mov_b32_e32 v28, v200
	v_mov_b32_e32 v29, v201
	v_mov_b32_e32 v30, v202
	v_mov_b32_e32 v31, v203
	s_cmp_ge_u32 s11, 8
	s_cbranch_scc0 .Lbs_nopre
.Lcip_pre:
	s_add_i32 s4, s30, 0
	s_mul_hi_u32 s6, s4, 0x33333334
	s_mul_i32 s6, s6, 5
	s_sub_i32 s4, s4, s6
	s_mul_i32 s6, s4, 0x6c00
	s_add_i32 s6, s6, 0xffffc800
	s_mul_i32 s5, s4, 0x2400
	s_cmp_gt_u32 s4, 1
	s_cselect_b32 s5, s6, s5
	v_add_u32_e32 v234, s5, v123
	ds_write_b128 v234, v[206:209]
	ds_write_b128 v234, v[210:213] offset:18432
	s_add_i32 s4, s30, 1
	s_mul_hi_u32 s6, s4, 0x33333334
	s_mul_i32 s6, s6, 5
	s_sub_i32 s4, s4, s6
	s_mul_i32 s6, s4, 0x6c00
	s_add_i32 s6, s6, 0xffffc800
	s_mul_i32 s5, s4, 0x2400
	s_cmp_gt_u32 s4, 1
	s_cselect_b32 s5, s6, s5
	v_add_u32_e32 v234, s5, v123
	ds_write_b128 v234, v[214:217]
	ds_write_b128 v234, v[218:221] offset:18432
	s_add_i32 s4, s30, 2
	s_mul_hi_u32 s6, s4, 0x33333334
	s_mul_i32 s6, s6, 5
	s_sub_i32 s4, s4, s6
	s_mul_i32 s6, s4, 0x6c00
	s_add_i32 s6, s6, 0xffffc800
	s_mul_i32 s5, s4, 0x2400
	s_cmp_gt_u32 s4, 1
	s_cselect_b32 s5, s6, s5
	v_add_u32_e32 v234, s5, v123
	ds_write_b128 v234, v[222:225]
	ds_write_b128 v234, v[226:229] offset:18432

.LBB0_1044:
	s_add_i32 s29, s30, 2
	s_cmp_ge_i32 s29, s2
	s_cselect_b64 s[0:1], -1, 0
	s_and_b64 vcc, exec, s[0:1]
	s_cmp_ge_u32 s11, 8
	s_cselect_b32 s4, 3, 0
	s_add_i32 s4, s4, s30
	s_mul_hi_u32 s6, s4, 0x33333334
	s_mul_i32 s6, s6, 5
	s_sub_i32 s4, s4, s6
	s_mul_i32 s6, s4, 0x6c00
	s_add_i32 s6, s6, 0xffffc800
	s_mul_i32 s5, s4, 0x2400
	s_cmp_gt_u32 s4, 1
	s_cselect_b32 s5, s6, s5
	v_add_u32_e32 v234, s5, v123
	s_waitcnt vmcnt(3)
	ds_write_b128 v234, v[16:19]
	s_waitcnt vmcnt(2)
	ds_write_b128 v234, v[20:23] offset:18432
	s_waitcnt lgkmcnt(0)
	s_barrier
	s_add_i32 s4, s30, 1
	s_cmp_ge_i32 s4, s2
	s_cbranch_scc1 .Lnpf_a
	v_add_co_u32_e32 v20, vcc, 0xfffb0000, v140
	s_nop 1
	v_addc_co_u32_e32 v21, vcc, -1, v141, vcc
	global_load_dwordx4 v[16:19], v[20:21], off offset:-1536
	s_nop 0
	global_load_dwordx4 v[20:23], v[20:21], off
.Lnpf_ret_a:
	s_cmp_ge_u32 s11, 8
	s_cselect_b32 s4, s13, 0
	s_add_i32 s4, s4, s30
	s_mul_hi_u32 s6, s4, 0x33333334
	s_mul_i32 s6, s6, 5
	s_sub_i32 s4, s4, s6
	s_mul_i32 s6, s4, 0x6c00
	s_add_i32 s6, s6, 0xffffc800
	s_mul_i32 s5, s4, 0x2400
	s_cmp_gt_u32 s4, 1
	s_cselect_b32 s5, s6, s5
	v_add_u32_e32 v235, s5, v125
	v_add_u32_e32 v236, s5, v143

.LBB0_1057:
	s_add_i32 s5, s30, 3
	s_cmp_ge_i32 s5, s2
	s_cmp_ge_u32 s11, 8
	s_cselect_b32 s5, 4, 1
	s_add_i32 s5, s5, s30
	s_mul_hi_u32 s7, s5, 0x33333334
	s_mul_i32 s7, s7, 5
	s_sub_i32 s5, s5, s7
	s_mul_i32 s7, s5, 0x6c00
	s_add_i32 s7, s7, 0xffffc800
	s_mul_i32 s6, s5, 0x2400
	s_cmp_gt_u32 s5, 1
	s_cselect_b32 s6, s7, s6
	s_add_i32 s6, s6, 0xffffdc00
	v_add_u32_e32 v234, s6, v123
	s_waitcnt vmcnt(3)
	ds_write_b128 v234, v[24:27] offset:9216
	s_waitcnt vmcnt(2)
	ds_write_b128 v234, v[28:31] offset:27648
	s_waitcnt lgkmcnt(0)
	s_barrier
	s_and_b64 vcc, exec, s[0:1]
	s_cbranch_vccnz .Lnpf_b
	global_load_dwordx4 v[24:27], v[140:141], off offset:-1536
	global_load_dwordx4 v[28:31], v[140:141], off
.Lnpf_ret_b:
	s_cmp_ge_u32 s11, 8
	s_cselect_b32 s5, s13, 0
	s_add_i32 s5, s5, s30
	s_add_i32 s5, s5, 1
	s_mul_hi_u32 s7, s5, 0x33333334
	s_mul_i32 s7, s7, 5
	s_sub_i32 s5, s5, s7
	s_mul_i32 s7, s5, 0x6c00
	s_add_i32 s7, s7, 0xffffc800
	s_mul_i32 s6, s5, 0x2400
	s_cmp_gt_u32 s5, 1
	s_cselect_b32 s6, s7, s6
	s_add_i32 s6, s6, 0xffffdc00
	v_add_u32_e32 v235, s6, v125
	v_add_u32_e32 v236, s6, v143

.Lnpf_a:
	s_add_i32 s9, s26, s90
	s_cmpk_gt_i32 s9, 0x5ff
	s_cbranch_scc1 .Lnpf_ret_a
	s_mul_hi_i32 s5, s9, 0x2aaaaaab
	s_ashr_i32 s6, s5, 1
	s_mul_i32 s7, s6, 12
	s_sub_i32 s7, s9, s7
	s_and_b32 s8, s6, 15
	s_ashr_i32 s5, s5, 5
	s_mul_i32 s100, s7, 0xc0
	s_mov_b32 s101, 0
	v_lshl_add_u64 v[246:247], s[100:101], 2, v[126:127]
	s_and_saveexec_b64 s[100:101], s[36:37]
	global_load_dword v237, v[246:247], off
	s_mov_b64 exec, s[100:101]
	s_lshl_b32 s4, s5, 12
	s_lshl_b32 s6, s8, 8
	s_or_b32 s6, s4, s6
	s_add_i32 s6, s6, s14
	s_mul_i32 s6, s6, 0x1400
	s_lshl_b32 s9, s7, 7
	s_add_i32 s6, s6, s9
	v_add3_u32 v246, v152, v130, s6
	global_load_dwordx4 v[176:179], v246, s[60:61]
	global_load_dwordx4 v[180:183], v246, s[60:61] offset:64
	v_add_u32_e32 v246, 0x14000, v246
	global_load_dwordx4 v[184:187], v246, s[60:61]
	global_load_dwordx4 v[196:199], v246, s[60:61] offset:64
	s_lshl_b32 s6, s8, 2
	s_add_i32 s6, s6, -8
	s_cmp_gt_u32 s8, 1
	s_cselect_b32 s6, s6, 0
	s_lshl_b32 s6, s6, 6
	s_add_i32 s6, s6, s4
	v_add_u32_e32 v246, s6, v114
	v_mul_lo_u32 v246, v246, s40
	v_or_b32_e32 v246, v246, v112
	v_lshl_add_u32 v246, v246, 1, s9
	s_mov_b32 s100, s94
	s_mov_b32 s101, s19
	s_mov_b32 s4, s31
	s_mov_b32 s5, s33
	s_cmp_gt_u32 s8, 1
	s_cbranch_scc0 .Lnpf_ns_a
	global_load_dwordx4 v[206:209], v246, s[100:101]
	global_load_dwordx4 v[210:213], v246, s[4:5]
	v_add_u32_e32 v246, 0x50000, v246
	global_load_dwordx4 v[214:217], v246, s[100:101]
	global_load_dwordx4 v[218:221], v246, s[4:5]
	v_add_u32_e32 v246, 0x50000, v246
	global_load_dwordx4 v[222:225], v246, s[100:101]
	global_load_dwordx4 v[226:229], v246, s[4:5]
	v_add_u32_e32 v246, 0x50000, v246
.Lnpf_ns_a:
	global_load_dwordx4 v[238:241], v246, s[100:101]
	global_load_dwordx4 v[242:245], v246, s[4:5]
	v_add_u32_e32 v246, 0x50000, v246
	global_load_dwordx4 v[230:233], v246, s[100:101]
	global_load_dwordx4 v[200:203], v246, s[4:5]
	s_branch .Lnpf_ret_a

.Lnpf_ns_b:
	global_load_dwordx4 v[238:241], v246, s[100:101]
	global_load_dwordx4 v[242:245], v246, s[4:5]
	v_add_u32_e32 v246, 0x50000, v246
	global_load_dwordx4 v[230:233], v246, s[100:101]
	global_load_dwordx4 v[200:203], v246, s[4:5]
	s_add_i32 s4, s30, 1
	s_branch .Lnpf_ret_b
